# v26 + tile swizzle group division by constant 4 as shift/mask (13 GEMM tile loops)
# speedup vs baseline: 1.0610x; 1.0010x over previous
;     __device__ __forceinline__ bool next(int i, Unit& u) const {
;     ...
;         int wgid = (int)L; { const int q = nwg / NXCD, r = nwg % NXCD, xcd = wgid % NXCD, off = wgid / NXCD; wgid = (xcd < r ? xcd * (q + 1) : r * (q + 1) + (xcd - r) * q) + off; }
;         const int nig = wgm * nN, gid = wgid / nig, fm = gid * wgm, gsz = (nM - fm) < wgm ? (nM - fm) : wgm;
;         u.pm = fm + ((wgid % nig) % gsz); u.pn = (wgid % nig) / gsz; u.z = 0; return true;
.LBB0_174:
	s_add_i32 s50, s56, 1
	s_mul_i32 s5, s50, s68
	s_mul_hi_i32 s4, s50, s68
	s_add_u32 s20, s5, s2
	s_addc_u32 s21, s4, s3
	v_cmp_gt_i64_e64 s[4:5], s[20:21], v[142:143]
	v_cmp_lt_i64_e64 s[6:7], s[20:21], v[140:141]
	s_and_b64 vcc, exec, s[4:5]
	s_cbranch_vccnz .LBB0_176
	s_ashr_i32 s9, s20, 31
	s_lshr_b32 s9, s9, 29
	s_add_i32 s9, s20, s9
	s_ashr_i32 s16, s9, 3
	s_and_b32 s9, s9, -8
	s_sub_i32 s9, s20, s9
	s_cmp_lt_i32 s9, 0
	s_cselect_b32 s17, s34, 0x2c0
	s_mul_i32 s9, s17, s9
	s_add_i32 s9, s9, s16
	s_mul_hi_i32 s16, s9, 0x2e8ba2e9
	s_lshr_b32 s17, s16, 31
	s_ashr_i32 s16, s16, 5
	s_add_i32 s16, s16, s17
	s_lshl_b32 s17, s16, 2
	s_sub_i32 s18, 0x80, s17
	s_min_i32 s18, s18, 4
	s_mulk_i32 s16, 0xb0
	s_sub_i32 s9, s9, s16
	s_ashr_i32 s16, s9, 2
	s_and_b32 s9, s9, 3
	s_add_i32 s18, s9, s17

;     __device__ __forceinline__ bool next(int i, Unit& u) const {
;     ...
;         int wgid = (int)L; { const int q = nwg / NXCD, r = nwg % NXCD, xcd = wgid % NXCD, off = wgid / NXCD; wgid = (xcd < r ? xcd * (q + 1) : r * (q + 1) + (xcd - r) * q) + off; }
;         const int nig = wgm * nN, gid = wgid / nig, fm = gid * wgm, gsz = (nM - fm) < wgm ? (nM - fm) : wgm;
;         u.pm = fm + ((wgid % nig) % gsz); u.pn = (wgid % nig) / gsz; u.z = 0; return true;
.LBB0_249:
	s_ashr_i32 s6, s11, 3
	s_add_i32 s6, s19, s6
	s_ashr_i32 s7, s6, 31
	s_lshr_b32 s7, s7, 27
	s_add_i32 s7, s6, s7
	s_ashr_i32 s11, s7, 5
	s_lshl_b32 s11, s11, 2
	s_sub_i32 s18, 0x80, s11
	s_min_i32 s18, s18, 4
	s_andn2_b32 s7, s7, 31
	s_sub_i32 s6, s6, s7
	s_ashr_i32 s65, s6, 2
	s_and_b32 s6, s6, 3
	s_add_i32 s66, s11, s6
	s_lshl_b32 s7, s65, 2

;     __device__ __forceinline__ bool next(int i, Unit& u) const {
;     ...
;         int wgid = (int)L; { const int q = nwg / NXCD, r = nwg % NXCD, xcd = wgid % NXCD, off = wgid / NXCD; wgid = (xcd < r ? xcd * (q + 1) : r * (q + 1) + (xcd - r) * q) + off; }
;         const int nig = wgm * nN, gid = wgid / nig, fm = gid * wgm, gsz = (nM - fm) < wgm ? (nM - fm) : wgm;
;         u.pm = fm + ((wgid % nig) % gsz); u.pn = (wgid % nig) / gsz; u.z = 0; return true;
.LBB0_375:
	s_add_i32 s57, s57, 1
	s_mul_i32 s4, s57, s85
	s_mul_hi_u32 s5, s57, s86
	s_add_i32 s5, s5, s4
	s_mul_i32 s4, s57, s86
	s_add_u32 s58, s4, s2
	s_addc_u32 s59, s5, s3
	v_cmp_gt_i64_e64 s[4:5], s[58:59], v[214:215]
	s_and_b64 vcc, exec, s[4:5]
	s_cbranch_vccnz .LBB0_377
	s_ashr_i32 s7, s58, 31
	s_lshr_b32 s7, s7, 29
	s_add_i32 s7, s58, s7
	s_ashr_i32 s10, s7, 3
	s_and_b32 s7, s7, -8
	s_sub_i32 s7, s58, s7
	s_cmp_lt_i32 s7, 0
	s_movk_i32 s11, 0x141
	s_cselect_b32 s11, s11, 0x140
	s_mul_i32 s7, s11, s7
	s_add_i32 s7, s7, s10
	s_mul_hi_i32 s10, s7, 0x66666667
	s_lshr_b32 s11, s10, 31
	s_ashr_i32 s10, s10, 5
	s_add_i32 s10, s10, s11
	s_lshl_b32 s11, s10, 2
	s_sub_i32 s34, 0x80, s11
	s_min_i32 s34, s34, 4
	s_mulk_i32 s10, 0x50
	s_sub_i32 s7, s7, s10
	s_ashr_i32 s38, s7, 2
	s_and_b32 s7, s7, 3
	s_add_i32 s52, s7, s11
	s_lshl_b32 s10, s38, 2

;     __device__ __forceinline__ bool next(int i, Unit& u) const {
;     ...
;         int wgid = (int)L; { const int q = nwg / NXCD, r = nwg % NXCD, xcd = wgid % NXCD, off = wgid / NXCD; wgid = (xcd < r ? xcd * (q + 1) : r * (q + 1) + (xcd - r) * q) + off; }
;         const int nig = wgm * nN, gid = wgid / nig, fm = gid * wgm, gsz = (nM - fm) < wgm ? (nM - fm) : wgm;
;         u.pm = fm + ((wgid % nig) % gsz); u.pn = (wgid % nig) / gsz; u.z = 0; return true;
.LBB0_1965:
	s_ashr_i32 s11, s11, 3
	s_add_i32 s11, s19, s11
	s_ashr_i32 s16, s11, 31
	s_lshr_b32 s16, s16, 27
	s_add_i32 s16, s11, s16
	s_ashr_i32 s17, s16, 5
	s_lshl_b32 s17, s17, 2
	s_sub_i32 s18, 0x80, s17
	s_min_i32 s18, s18, 4
	s_andn2_b32 s16, s16, 31
	s_sub_i32 s11, s11, s16
	s_ashr_i32 s16, s11, 2
	s_and_b32 s11, s11, 3
	s_add_i32 s18, s17, s11

;     __device__ __forceinline__ bool next(int i, Unit& u) const {
;     ...
;         int wgid = (int)L; { const int q = nwg / NXCD, r = nwg % NXCD, xcd = wgid % NXCD, off = wgid / NXCD; wgid = (xcd < r ? xcd * (q + 1) : r * (q + 1) + (xcd - r) * q) + off; }
;         const int nig = wgm * nN, gid = wgid / nig, fm = gid * wgm, gsz = (nM - fm) < wgm ? (nM - fm) : wgm;
;         u.pm = fm + ((wgid % nig) % gsz); u.pn = (wgid % nig) / gsz; u.z = 0; return true;
.LBB0_2085:
	s_add_i32 s50, s57, 1
	s_mul_i32 s9, s50, s68
	s_mul_hi_i32 s8, s50, s68
	s_add_u32 s22, s9, s2
	s_addc_u32 s23, s8, s3
	v_cmp_gt_i64_e64 s[8:9], s[22:23], v[142:143]
	v_cmp_lt_i64_e64 s[10:11], s[22:23], v[140:141]
	s_and_b64 vcc, exec, s[8:9]
	s_cbranch_vccnz .LBB0_2087
	s_ashr_i32 s13, s22, 31
	s_lshr_b32 s13, s13, 29
	s_add_i32 s13, s22, s13
	s_ashr_i32 s18, s13, 3
	s_and_b32 s13, s13, -8
	s_sub_i32 s13, s22, s13
	s_cmp_lt_i32 s13, 0
	s_cselect_b32 s19, s35, 0x2c0
	s_mul_i32 s13, s19, s13
	s_add_i32 s13, s13, s18
	s_mul_hi_i32 s18, s13, 0x2e8ba2e9
	s_lshr_b32 s19, s18, 31
	s_ashr_i32 s18, s18, 5
	s_add_i32 s18, s18, s19
	s_lshl_b32 s19, s18, 2
	s_sub_i32 s20, 0x80, s19
	s_min_i32 s20, s20, 4
	s_mulk_i32 s18, 0xb0
	s_sub_i32 s13, s13, s18
	s_ashr_i32 s18, s13, 2
	s_and_b32 s13, s13, 3
	s_add_i32 s20, s13, s19

;     __device__ __forceinline__ bool next(int i, Unit& u) const {
;     ...
;         int wgid = (int)L; { const int q = nwg / NXCD, r = nwg % NXCD, xcd = wgid % NXCD, off = wgid / NXCD; wgid = (xcd < r ? xcd * (q + 1) : r * (q + 1) + (xcd - r) * q) + off; }
;         const int nig = wgm * nN, gid = wgid / nig, fm = gid * wgm, gsz = (nM - fm) < wgm ? (nM - fm) : wgm;
;         u.pm = fm + ((wgid % nig) % gsz); u.pn = (wgid % nig) / gsz; u.z = 0; return true;
.LBB0_2160:
	s_ashr_i32 s10, s15, 3
	s_add_i32 s10, s21, s10
	s_ashr_i32 s11, s10, 31
	s_lshr_b32 s11, s11, 27
	s_add_i32 s11, s10, s11
	s_ashr_i32 s15, s11, 5
	s_lshl_b32 s15, s15, 2
	s_sub_i32 s20, 0x80, s15
	s_min_i32 s20, s20, 4
	s_andn2_b32 s11, s11, 31
	s_sub_i32 s10, s10, s11
	s_ashr_i32 s65, s10, 2
	s_and_b32 s10, s10, 3
	s_add_i32 s66, s15, s10
	s_lshl_b32 s11, s65, 2

;     __device__ __forceinline__ bool next(int i, Unit& u) const {
;     ...
;         int wgid = (int)L; { const int q = nwg / NXCD, r = nwg % NXCD, xcd = wgid % NXCD, off = wgid / NXCD; wgid = (xcd < r ? xcd * (q + 1) : r * (q + 1) + (xcd - r) * q) + off; }
;         const int nig = wgm * nN, gid = wgid / nig, fm = gid * wgm, gsz = (nM - fm) < wgm ? (nM - fm) : wgm;
;         u.pm = fm + ((wgid % nig) % gsz); u.pn = (wgid % nig) / gsz; u.z = 0; return true;
.LBB0_2485:
	s_add_i32 s50, s43, 1
	s_mul_i32 s9, s50, s68
	s_mul_hi_i32 s8, s50, s68
	s_add_u32 s14, s9, s2
	s_addc_u32 s15, s8, s3
	v_cmp_gt_i64_e64 s[8:9], s[14:15], v[140:141]
	v_cmp_lt_i64_e64 s[10:11], s[14:15], v[138:139]
	s_and_b64 vcc, exec, s[8:9]
	s_cbranch_vccnz .LBB0_2487
	s_ashr_i32 s15, s14, 31
	s_lshr_b32 s15, s15, 29
	s_add_i32 s15, s14, s15
	s_ashr_i32 s16, s15, 3
	s_and_b32 s15, s15, -8
	s_sub_i32 s14, s14, s15
	s_cmp_lt_i32 s14, 0
	s_movk_i32 s15, 0x51
	s_cselect_b32 s15, s15, 0x50
	s_mul_i32 s14, s15, s14
	s_add_i32 s14, s14, s16
	s_mul_hi_i32 s15, s14, 0x66666667
	s_lshr_b32 s16, s15, 31
	s_ashr_i32 s15, s15, 3
	s_add_i32 s15, s15, s16
	s_lshl_b32 s16, s15, 2
	s_sub_i32 s17, 0x80, s16
	s_min_i32 s17, s17, 4
	s_mul_i32 s15, s15, 20
	s_sub_i32 s14, s14, s15
	s_ashr_i32 s58, s14, 2
	s_and_b32 s14, s14, 3
	s_add_i32 s64, s14, s16
	s_lshl_b32 s15, s58, 2

;     __device__ __forceinline__ bool next(int i, Unit& u) const {
;     ...
;         int wgid = (int)L; { const int q = nwg / NXCD, r = nwg % NXCD, xcd = wgid % NXCD, off = wgid / NXCD; wgid = (xcd < r ? xcd * (q + 1) : r * (q + 1) + (xcd - r) * q) + off; }
;         const int nig = wgm * nN, gid = wgid / nig, fm = gid * wgm, gsz = (nM - fm) < wgm ? (nM - fm) : wgm;
;         u.pm = fm + ((wgid % nig) % gsz); u.pn = (wgid % nig) / gsz; u.z = 0; return true;
.LBB0_2708:
	s_ashr_i32 s12, s14, 3
	s_add_i32 s12, s18, s12
	s_ashr_i32 s13, s12, 31
	s_lshr_b32 s13, s13, 26
	s_add_i32 s13, s12, s13
	s_ashr_i32 s14, s13, 6
	s_lshl_b32 s14, s14, 2
	s_sub_i32 s15, 0x80, s14
	s_min_i32 s15, s15, 4
	s_andn2_b32 s13, s13, 63
	s_sub_i32 s13, s12, s13
	s_ashr_i32 s12, s13, 2
	s_and_b32 s13, s13, 3
	s_add_i32 s14, s14, s13
	s_lshl_b32 s15, s12, 2

;     __device__ __forceinline__ bool next(int i, Unit& u) const {
;     ...
;         int wgid = (int)L; { const int q = nwg / NXCD, r = nwg % NXCD, xcd = wgid % NXCD, off = wgid / NXCD; wgid = (xcd < r ? xcd * (q + 1) : r * (q + 1) + (xcd - r) * q) + off; }
;         const int nig = wgm * nN, gid = wgid / nig, fm = gid * wgm, gsz = (nM - fm) < wgm ? (nM - fm) : wgm;
;         u.pm = fm + ((wgid % nig) % gsz); u.pn = (wgid % nig) / gsz; u.z = 0; return true;
.LBB0_2962:
	s_ashr_i32 s13, s13, 3
	s_add_i32 s13, s21, s13
	s_ashr_i32 s18, s13, 31
	s_lshr_b32 s18, s18, 27
	s_add_i32 s18, s13, s18
	s_ashr_i32 s19, s18, 5
	s_lshl_b32 s19, s19, 2
	s_sub_i32 s20, 0x80, s19
	s_min_i32 s20, s20, 4
	s_andn2_b32 s18, s18, 31
	s_sub_i32 s13, s13, s18
	s_ashr_i32 s18, s13, 2
	s_and_b32 s13, s13, 3
	s_add_i32 s20, s19, s13

;     __device__ __forceinline__ bool next(int i, Unit& u) const {
;     ...
;         int wgid = (int)L; { const int q = nwg / NXCD, r = nwg % NXCD, xcd = wgid % NXCD, off = wgid / NXCD; wgid = (xcd < r ? xcd * (q + 1) : r * (q + 1) + (xcd - r) * q) + off; }
;         const int nig = wgm * nN, gid = wgid / nig, fm = gid * wgm, gsz = (nM - fm) < wgm ? (nM - fm) : wgm;
;         u.pm = fm + ((wgid % nig) % gsz); u.pn = (wgid % nig) / gsz; u.z = 0; return true;
.LBB0_3082:
	s_add_i32 s63, s47, 1
	s_mul_i32 s7, s63, s68
	s_mul_hi_i32 s6, s63, s68
	s_add_u32 s20, s7, s2
	s_addc_u32 s21, s6, s3
	v_cmp_gt_i64_e64 s[6:7], s[20:21], v[142:143]
	v_cmp_lt_i64_e64 s[8:9], s[20:21], v[140:141]
	s_and_b64 vcc, exec, s[6:7]
	s_cbranch_vccnz .LBB0_3084
	s_ashr_i32 s11, s20, 31
	s_lshr_b32 s11, s11, 29
	s_add_i32 s11, s20, s11
	s_ashr_i32 s16, s11, 3
	s_and_b32 s11, s11, -8
	s_sub_i32 s11, s20, s11
	s_cmp_lt_i32 s11, 0
	s_cselect_b32 s17, s35, 0x2c0
	s_mul_i32 s11, s17, s11
	s_add_i32 s11, s11, s16
	s_mul_hi_i32 s16, s11, 0x2e8ba2e9
	s_lshr_b32 s17, s16, 31
	s_ashr_i32 s16, s16, 5
	s_add_i32 s16, s16, s17
	s_lshl_b32 s17, s16, 2
	s_sub_i32 s18, 0x80, s17
	s_min_i32 s18, s18, 4
	s_mulk_i32 s16, 0xb0
	s_sub_i32 s11, s11, s16
	s_ashr_i32 s16, s11, 2
	s_and_b32 s11, s11, 3
	s_add_i32 s18, s11, s17

;     __device__ __forceinline__ bool next(int i, Unit& u) const {
;     ...
;         int wgid = (int)L; { const int q = nwg / NXCD, r = nwg % NXCD, xcd = wgid % NXCD, off = wgid / NXCD; wgid = (xcd < r ? xcd * (q + 1) : r * (q + 1) + (xcd - r) * q) + off; }
;         const int nig = wgm * nN, gid = wgid / nig, fm = gid * wgm, gsz = (nM - fm) < wgm ? (nM - fm) : wgm;
;         u.pm = fm + ((wgid % nig) % gsz); u.pn = (wgid % nig) / gsz; u.z = 0; return true;
.LBB0_3157:
	s_ashr_i32 s6, s11, 3
	s_add_i32 s6, s17, s6
	s_ashr_i32 s7, s6, 31
	s_lshr_b32 s7, s7, 27
	s_add_i32 s7, s6, s7
	s_ashr_i32 s11, s7, 5
	s_lshl_b32 s11, s11, 2
	s_sub_i32 s16, 0x80, s11
	s_min_i32 s16, s16, 4
	s_andn2_b32 s7, s7, 31
	s_sub_i32 s6, s6, s7
	s_ashr_i32 s53, s6, 2
	s_and_b32 s6, s6, 3
	s_add_i32 s54, s11, s6
	s_lshl_b32 s7, s53, 2
